# stack: combo + M1 H stores lane-permuted (ds_bpermute) into contiguous 64B pieces + final-norm 8-row fast path
# baseline (speedup 1.0000x reference)
.Lpf_skip:
	v_mbcnt_lo_u32_b32 v196, -1, 0
	v_mbcnt_hi_u32_b32 v196, -1, v196
	v_and_b32_e32 v197, 3, v196
	v_lshrrev_b32_e32 v198, 2, v196
	v_and_b32_e32 v199, 15, v196
	v_sub_u32_e32 v198, v198, v199
	v_lshrrev_b32_e32 v199, 4, v196
	v_sub_u32_e32 v199, v197, v199
	v_lshlrev_b32_e32 v198, 13, v198
	v_lshl_add_u32 v198, v199, 4, v198
	v_ashrrev_i32_e32 v199, 31, v198
	v_lshl_add_u64 v[226:227], v[198:199], 0, v[154:155]
	v_lshlrev_b32_e32 v197, 4, v197
	v_lshrrev_b32_e32 v196, 2, v196
	v_or_b32_e32 v196, v197, v196
	v_lshlrev_b32_e32 v196, 2, v196
	s_mov_b64 s[88:89], 0x20000
	v_fmamk_f32 v173, v173, 0x3a800000, v228
	v_cmp_gt_f32_e32 vcc, s1, v173
	v_mul_f32_e32 v174, 0x4f800000, v173
	s_nop 0
	v_cndmask_b32_e32 v173, v173, v174, vcc
	v_sqrt_f32_e32 v174, v173
	s_nop 0
	v_add_u32_e32 v175, -1, v174
	v_fma_f32 v178, -v175, v174, v173
	v_cmp_ge_f32_e64 s[8:9], 0, v178
	v_add_u32_e32 v178, 1, v174
	s_nop 0
	v_cndmask_b32_e64 v175, v174, v175, s[8:9]
	v_fma_f32 v174, -v178, v174, v173
	v_cmp_lt_f32_e64 s[8:9], 0, v174
	s_nop 1
	v_cndmask_b32_e64 v174, v175, v178, s[8:9]
	v_mul_f32_e32 v175, 0x37800000, v174
	v_cndmask_b32_e32 v174, v174, v175, vcc
	v_cmp_class_f32_e32 vcc, v173, v229
	s_nop 1
	v_cndmask_b32_e32 v173, v174, v173, vcc
	v_div_scale_f32 v174, s[8:9], v173, v173, 1.0
	v_rcp_f32_e32 v175, v174
	s_nop 0
	v_fma_f32 v178, -v174, v175, 1.0
	v_fmac_f32_e32 v175, v178, v175
	v_div_scale_f32 v178, vcc, 1.0, v173, 1.0
	v_mul_f32_e32 v179, v178, v175
	v_fma_f32 v180, -v174, v179, v178
	v_fmac_f32_e32 v179, v180, v175
	v_fma_f32 v174, -v174, v179, v178
	v_div_fmas_f32 v174, v174, v175, v179
	v_div_fixup_f32 v174, v174, v173, 1.0
	v_pk_fma_f32 v[136:137], v[136:137], v[174:175], v[88:89] op_sel_hi:[1,0,1]
	v_pk_fma_f32 v[142:143], v[142:143], v[174:175], v[94:95] op_sel_hi:[1,0,1]
	v_pk_fma_f32 v[140:141], v[140:141], v[174:175], v[92:93] op_sel_hi:[1,0,1]
	v_pk_fma_f32 v[138:139], v[138:139], v[174:175], v[90:91] op_sel_hi:[1,0,1]
	v_max_f32_e32 v136, 0, v136
	v_max_f32_e32 v137, 0, v137
	v_max_f32_e32 v140, 0, v140
	v_max_f32_e32 v141, 0, v141
	v_pk_mul_f32 v[178:179], v[136:137], v[136:137]
	v_max_f32_e32 v136, 0, v142
	v_max_f32_e32 v138, 0, v138
	v_max_f32_e32 v137, 0, v143
	v_max_f32_e32 v139, 0, v139
	v_pk_mul_f32 v[140:141], v[140:141], v[140:141]
	v_pk_mul_f32 v[142:143], v[136:137], v[136:137]
	v_pk_mul_f32 v[180:181], v[138:139], v[138:139]
	v_pk_fma_f32 v[128:129], v[128:129], v[174:175], v[80:81] op_sel_hi:[1,0,1]
	v_cvt_pk_bf16_f32 v136, v140, v141
	v_cvt_pk_bf16_f32 v137, v142, v143
	v_cvt_pk_bf16_f32 v138, v178, v179
	v_cvt_pk_bf16_f32 v139, v180, v181
	v_pk_fma_f32 v[134:135], v[134:135], v[174:175], v[86:87] op_sel_hi:[1,0,1]
	v_pk_fma_f32 v[132:133], v[132:133], v[174:175], v[84:85] op_sel_hi:[1,0,1]
	v_pk_fma_f32 v[130:131], v[130:131], v[174:175], v[82:83] op_sel_hi:[1,0,1]
	v_max_f32_e32 v128, 0, v128
	v_max_f32_e32 v129, 0, v129
	ds_bpermute_b32 v192, v196, v136
	ds_bpermute_b32 v193, v196, v137
	ds_bpermute_b32 v194, v196, v138
	ds_bpermute_b32 v195, v196, v139
	s_waitcnt lgkmcnt(0)
	global_store_dwordx4 v[226:227], v[192:195], off
	v_max_f32_e32 v132, 0, v132
	v_max_f32_e32 v133, 0, v133
	v_pk_mul_f32 v[136:137], v[128:129], v[128:129]
	v_max_f32_e32 v128, 0, v134
	v_max_f32_e32 v130, 0, v130
	v_max_f32_e32 v129, 0, v135
	v_max_f32_e32 v131, 0, v131
	v_pk_mul_f32 v[132:133], v[132:133], v[132:133]
	v_pk_mul_f32 v[134:135], v[128:129], v[128:129]
	v_pk_mul_f32 v[138:139], v[130:131], v[130:131]
	v_cvt_pk_bf16_f32 v128, v132, v133
	v_cvt_pk_bf16_f32 v129, v134, v135
	v_cvt_pk_bf16_f32 v130, v136, v137
	v_cvt_pk_bf16_f32 v131, v138, v139
	ds_bpermute_b32 v192, v196, v128
	ds_bpermute_b32 v193, v196, v129
	ds_bpermute_b32 v194, v196, v130
	ds_bpermute_b32 v195, v196, v131
	s_waitcnt lgkmcnt(0)
	global_store_dwordx4 v[226:227], v[192:195], off offset:256
	v_lshl_add_u64 v[226:227], v[226:227], 0, s[88:89]
	s_nop 1
	v_fmamk_f32 v130, v172, 0x3a800000, v228
	v_cmp_gt_f32_e32 vcc, s1, v130
	v_mul_f32_e32 v131, 0x4f800000, v130
	v_lshlrev_b64 v[128:129], 13, v[176:177]
	v_cndmask_b32_e32 v130, v130, v131, vcc
	v_sqrt_f32_e32 v131, v130
	v_lshl_add_u64 v[128:129], s[14:15], 0, v[128:129]
	v_lshl_add_u64 v[128:129], v[128:129], 0, v[158:159]
	v_add_u32_e32 v132, -1, v131
	v_fma_f32 v133, -v132, v131, v130
	v_cmp_ge_f32_e64 s[8:9], 0, v133
	v_add_u32_e32 v133, 1, v131
	s_nop 0
	v_cndmask_b32_e64 v132, v131, v132, s[8:9]
	v_fma_f32 v131, -v133, v131, v130
	v_cmp_lt_f32_e64 s[8:9], 0, v131
	s_nop 1
	v_cndmask_b32_e64 v131, v132, v133, s[8:9]
	v_mul_f32_e32 v132, 0x37800000, v131
	v_cndmask_b32_e32 v131, v131, v132, vcc
	v_cmp_class_f32_e32 vcc, v130, v229
	s_nop 1
	v_cndmask_b32_e32 v130, v131, v130, vcc
	v_div_scale_f32 v131, s[8:9], v130, v130, 1.0
	v_rcp_f32_e32 v132, v131
	s_nop 0
	v_fma_f32 v133, -v131, v132, 1.0
	v_fmac_f32_e32 v132, v133, v132
	v_div_scale_f32 v133, vcc, 1.0, v130, 1.0
	v_mul_f32_e32 v134, v133, v132
	v_fma_f32 v135, -v131, v134, v133
	v_fmac_f32_e32 v134, v135, v132
	v_fma_f32 v131, -v131, v134, v133
	v_div_fmas_f32 v131, v131, v132, v134
	v_div_fixup_f32 v130, v131, v130, 1.0
	v_pk_fma_f32 v[120:121], v[120:121], v[130:131], v[88:89] op_sel_hi:[1,0,1]
	v_pk_fma_f32 v[126:127], v[126:127], v[130:131], v[94:95] op_sel_hi:[1,0,1]
	v_pk_fma_f32 v[124:125], v[124:125], v[130:131], v[92:93] op_sel_hi:[1,0,1]
	v_pk_fma_f32 v[122:123], v[122:123], v[130:131], v[90:91] op_sel_hi:[1,0,1]
	v_max_f32_e32 v120, 0, v120
	v_max_f32_e32 v121, 0, v121
	v_max_f32_e32 v124, 0, v124
	v_max_f32_e32 v125, 0, v125
	v_pk_mul_f32 v[132:133], v[120:121], v[120:121]
	v_max_f32_e32 v120, 0, v126
	v_max_f32_e32 v122, 0, v122
	v_max_f32_e32 v121, 0, v127
	v_max_f32_e32 v123, 0, v123
	v_pk_mul_f32 v[124:125], v[124:125], v[124:125]
	v_pk_mul_f32 v[126:127], v[120:121], v[120:121]
	v_pk_mul_f32 v[134:135], v[122:123], v[122:123]
	v_pk_fma_f32 v[112:113], v[112:113], v[130:131], v[80:81] op_sel_hi:[1,0,1]
	v_cvt_pk_bf16_f32 v120, v124, v125
	v_cvt_pk_bf16_f32 v121, v126, v127
	v_cvt_pk_bf16_f32 v122, v132, v133
	v_cvt_pk_bf16_f32 v123, v134, v135
	v_pk_fma_f32 v[118:119], v[118:119], v[130:131], v[86:87] op_sel_hi:[1,0,1]
	v_pk_fma_f32 v[116:117], v[116:117], v[130:131], v[84:85] op_sel_hi:[1,0,1]
	v_pk_fma_f32 v[114:115], v[114:115], v[130:131], v[82:83] op_sel_hi:[1,0,1]
	v_max_f32_e32 v112, 0, v112
	v_max_f32_e32 v113, 0, v113
	ds_bpermute_b32 v192, v196, v120
	ds_bpermute_b32 v193, v196, v121
	ds_bpermute_b32 v194, v196, v122
	ds_bpermute_b32 v195, v196, v123
	s_waitcnt lgkmcnt(0)
	global_store_dwordx4 v[226:227], v[192:195], off
	v_max_f32_e32 v116, 0, v116
	v_max_f32_e32 v117, 0, v117
	v_pk_mul_f32 v[120:121], v[112:113], v[112:113]
	v_max_f32_e32 v112, 0, v118
	v_max_f32_e32 v114, 0, v114
	v_max_f32_e32 v113, 0, v119
	v_max_f32_e32 v115, 0, v115
	v_pk_mul_f32 v[116:117], v[116:117], v[116:117]
	v_pk_mul_f32 v[118:119], v[112:113], v[112:113]
	v_pk_mul_f32 v[122:123], v[114:115], v[114:115]
	v_cvt_pk_bf16_f32 v112, v116, v117
	v_cvt_pk_bf16_f32 v113, v118, v119
	v_cvt_pk_bf16_f32 v114, v120, v121
	v_cvt_pk_bf16_f32 v115, v122, v123
	ds_bpermute_b32 v192, v196, v112
	ds_bpermute_b32 v193, v196, v113
	ds_bpermute_b32 v194, v196, v114
	ds_bpermute_b32 v195, v196, v115
	s_waitcnt lgkmcnt(0)
	global_store_dwordx4 v[226:227], v[192:195], off offset:256
	v_lshl_add_u64 v[226:227], v[226:227], 0, s[88:89]
	s_nop 1
	v_fmamk_f32 v114, v171, 0x3a800000, v228
	v_cmp_gt_f32_e32 vcc, s1, v114
	v_mul_f32_e32 v115, 0x4f800000, v114
	v_lshlrev_b64 v[112:113], 13, v[160:161]
	v_cndmask_b32_e32 v114, v114, v115, vcc
	v_sqrt_f32_e32 v115, v114
	v_lshl_add_u64 v[112:113], s[14:15], 0, v[112:113]
	v_lshl_add_u64 v[112:113], v[112:113], 0, v[158:159]
	v_add_u32_e32 v116, -1, v115
	v_fma_f32 v117, -v116, v115, v114
	v_cmp_ge_f32_e64 s[8:9], 0, v117
	v_add_u32_e32 v117, 1, v115
	s_nop 0
	v_cndmask_b32_e64 v116, v115, v116, s[8:9]
	v_fma_f32 v115, -v117, v115, v114
	v_cmp_lt_f32_e64 s[8:9], 0, v115
	s_nop 1
	v_cndmask_b32_e64 v115, v116, v117, s[8:9]
	v_mul_f32_e32 v116, 0x37800000, v115
	v_cndmask_b32_e32 v115, v115, v116, vcc
	v_cmp_class_f32_e32 vcc, v114, v229
	s_nop 1
	v_cndmask_b32_e32 v114, v115, v114, vcc
	v_div_scale_f32 v115, s[8:9], v114, v114, 1.0
	v_rcp_f32_e32 v116, v115
	s_nop 0
	v_fma_f32 v117, -v115, v116, 1.0
	v_fmac_f32_e32 v116, v117, v116
	v_div_scale_f32 v117, vcc, 1.0, v114, 1.0
	v_mul_f32_e32 v118, v117, v116
	v_fma_f32 v119, -v115, v118, v117
	v_fmac_f32_e32 v118, v119, v116
	v_fma_f32 v115, -v115, v118, v117
	v_div_fmas_f32 v115, v115, v116, v118
	v_div_fixup_f32 v114, v115, v114, 1.0
	v_pk_fma_f32 v[104:105], v[104:105], v[114:115], v[88:89] op_sel_hi:[1,0,1]
	v_pk_fma_f32 v[110:111], v[110:111], v[114:115], v[94:95] op_sel_hi:[1,0,1]
	v_pk_fma_f32 v[108:109], v[108:109], v[114:115], v[92:93] op_sel_hi:[1,0,1]
	v_pk_fma_f32 v[106:107], v[106:107], v[114:115], v[90:91] op_sel_hi:[1,0,1]
	v_max_f32_e32 v104, 0, v104
	v_max_f32_e32 v105, 0, v105
	v_max_f32_e32 v108, 0, v108
	v_max_f32_e32 v109, 0, v109
	v_pk_mul_f32 v[116:117], v[104:105], v[104:105]
	v_max_f32_e32 v104, 0, v110
	v_max_f32_e32 v106, 0, v106
	v_max_f32_e32 v105, 0, v111
	v_max_f32_e32 v107, 0, v107
	v_pk_mul_f32 v[108:109], v[108:109], v[108:109]
	v_pk_mul_f32 v[110:111], v[104:105], v[104:105]
	v_pk_mul_f32 v[118:119], v[106:107], v[106:107]
	v_pk_fma_f32 v[96:97], v[96:97], v[114:115], v[80:81] op_sel_hi:[1,0,1]
	v_cvt_pk_bf16_f32 v104, v108, v109
	v_cvt_pk_bf16_f32 v105, v110, v111
	v_cvt_pk_bf16_f32 v106, v116, v117
	v_cvt_pk_bf16_f32 v107, v118, v119
	v_pk_fma_f32 v[102:103], v[102:103], v[114:115], v[86:87] op_sel_hi:[1,0,1]
	v_pk_fma_f32 v[100:101], v[100:101], v[114:115], v[84:85] op_sel_hi:[1,0,1]
	v_pk_fma_f32 v[98:99], v[98:99], v[114:115], v[82:83] op_sel_hi:[1,0,1]
	v_max_f32_e32 v96, 0, v96
	v_max_f32_e32 v97, 0, v97
	ds_bpermute_b32 v192, v196, v104
	ds_bpermute_b32 v193, v196, v105
	ds_bpermute_b32 v194, v196, v106
	ds_bpermute_b32 v195, v196, v107
	s_waitcnt lgkmcnt(0)
	global_store_dwordx4 v[226:227], v[192:195], off
	v_max_f32_e32 v100, 0, v100
	v_max_f32_e32 v101, 0, v101
	v_pk_mul_f32 v[104:105], v[96:97], v[96:97]
	v_max_f32_e32 v96, 0, v102
	v_max_f32_e32 v98, 0, v98
	v_max_f32_e32 v97, 0, v103
	v_max_f32_e32 v99, 0, v99
	v_pk_mul_f32 v[100:101], v[100:101], v[100:101]
	v_pk_mul_f32 v[102:103], v[96:97], v[96:97]
	v_pk_mul_f32 v[106:107], v[98:99], v[98:99]
	v_cvt_pk_bf16_f32 v96, v100, v101
	v_cvt_pk_bf16_f32 v97, v102, v103
	v_cvt_pk_bf16_f32 v98, v104, v105
	v_cvt_pk_bf16_f32 v99, v106, v107
	ds_bpermute_b32 v192, v196, v96
	ds_bpermute_b32 v193, v196, v97
	ds_bpermute_b32 v194, v196, v98
	ds_bpermute_b32 v195, v196, v99
	s_waitcnt lgkmcnt(0)
	global_store_dwordx4 v[226:227], v[192:195], off offset:256
	v_lshl_add_u64 v[226:227], v[226:227], 0, s[88:89]
	s_nop 1
	v_fmamk_f32 v98, v170, 0x3a800000, v228
	v_cmp_gt_f32_e32 vcc, s1, v98
	v_mul_f32_e32 v99, 0x4f800000, v98
	v_lshlrev_b64 v[96:97], 13, v[156:157]
	v_cndmask_b32_e32 v98, v98, v99, vcc
	v_sqrt_f32_e32 v99, v98
	v_lshl_add_u64 v[96:97], s[14:15], 0, v[96:97]
	v_lshl_add_u64 v[96:97], v[96:97], 0, v[158:159]
	v_add_u32_e32 v100, -1, v99
	v_fma_f32 v101, -v100, v99, v98
	v_cmp_ge_f32_e64 s[8:9], 0, v101
	v_add_u32_e32 v101, 1, v99
	s_nop 0
	v_cndmask_b32_e64 v100, v99, v100, s[8:9]
	v_fma_f32 v99, -v101, v99, v98
	v_cmp_lt_f32_e64 s[8:9], 0, v99
	s_nop 1
	v_cndmask_b32_e64 v99, v100, v101, s[8:9]
	v_mul_f32_e32 v100, 0x37800000, v99
	v_cndmask_b32_e32 v99, v99, v100, vcc
	v_cmp_class_f32_e32 vcc, v98, v229
	s_nop 1
	v_cndmask_b32_e32 v98, v99, v98, vcc
	v_div_scale_f32 v99, s[8:9], v98, v98, 1.0
	v_rcp_f32_e32 v100, v99
	s_mov_b64 s[8:9], 0x100000
	v_fma_f32 v101, -v99, v100, 1.0
	v_fmac_f32_e32 v100, v101, v100
	v_div_scale_f32 v101, vcc, 1.0, v98, 1.0
	v_mul_f32_e32 v102, v101, v100
	v_fma_f32 v103, -v99, v102, v101
	v_fmac_f32_e32 v102, v103, v100
	v_fma_f32 v99, -v99, v102, v101
	v_div_fmas_f32 v99, v99, v100, v102
	v_div_fixup_f32 v98, v99, v98, 1.0
	v_pk_fma_f32 v[72:73], v[72:73], v[98:99], v[88:89] op_sel_hi:[1,0,1]
	v_pk_fma_f32 v[78:79], v[78:79], v[98:99], v[94:95] op_sel_hi:[1,0,1]
	v_pk_fma_f32 v[76:77], v[76:77], v[98:99], v[92:93] op_sel_hi:[1,0,1]
	v_pk_fma_f32 v[74:75], v[74:75], v[98:99], v[90:91] op_sel_hi:[1,0,1]
	v_max_f32_e32 v72, 0, v72
	v_max_f32_e32 v73, 0, v73
	v_max_f32_e32 v76, 0, v76
	v_max_f32_e32 v77, 0, v77
	v_pk_mul_f32 v[100:101], v[72:73], v[72:73]
	v_max_f32_e32 v72, 0, v78
	v_max_f32_e32 v74, 0, v74
	v_max_f32_e32 v73, 0, v79
	v_max_f32_e32 v75, 0, v75
	v_pk_mul_f32 v[76:77], v[76:77], v[76:77]
	v_pk_mul_f32 v[78:79], v[72:73], v[72:73]
	v_pk_mul_f32 v[102:103], v[74:75], v[74:75]
	v_pk_fma_f32 v[64:65], v[64:65], v[98:99], v[80:81] op_sel_hi:[1,0,1]
	v_cvt_pk_bf16_f32 v72, v76, v77
	v_cvt_pk_bf16_f32 v73, v78, v79
	v_cvt_pk_bf16_f32 v74, v100, v101
	v_cvt_pk_bf16_f32 v75, v102, v103
	v_pk_fma_f32 v[70:71], v[70:71], v[98:99], v[86:87] op_sel_hi:[1,0,1]
	v_pk_fma_f32 v[68:69], v[68:69], v[98:99], v[84:85] op_sel_hi:[1,0,1]
	v_pk_fma_f32 v[66:67], v[66:67], v[98:99], v[82:83] op_sel_hi:[1,0,1]
	v_max_f32_e32 v64, 0, v64
	v_max_f32_e32 v65, 0, v65
	ds_bpermute_b32 v192, v196, v72
	ds_bpermute_b32 v193, v196, v73
	ds_bpermute_b32 v194, v196, v74
	ds_bpermute_b32 v195, v196, v75
	s_waitcnt lgkmcnt(0)
	global_store_dwordx4 v[226:227], v[192:195], off
	v_max_f32_e32 v68, 0, v68
	v_max_f32_e32 v69, 0, v69
	v_pk_mul_f32 v[72:73], v[64:65], v[64:65]
	v_max_f32_e32 v64, 0, v70
	v_max_f32_e32 v66, 0, v66
	v_max_f32_e32 v65, 0, v71
	v_max_f32_e32 v67, 0, v67
	v_pk_mul_f32 v[68:69], v[68:69], v[68:69]
	v_pk_mul_f32 v[70:71], v[64:65], v[64:65]
	v_pk_mul_f32 v[74:75], v[66:67], v[66:67]
	v_cvt_pk_bf16_f32 v64, v68, v69
	v_cvt_pk_bf16_f32 v65, v70, v71
	v_cvt_pk_bf16_f32 v66, v72, v73
	v_cvt_pk_bf16_f32 v67, v74, v75
	ds_bpermute_b32 v192, v196, v64
	ds_bpermute_b32 v193, v196, v65
	ds_bpermute_b32 v194, v196, v66
	ds_bpermute_b32 v195, v196, v67
	s_waitcnt lgkmcnt(0)
	global_store_dwordx4 v[226:227], v[192:195], off offset:256
	s_mov_b64 s[88:89], 0xa0000
	v_lshl_add_u64 v[226:227], v[226:227], 0, s[88:89]
	s_mov_b64 s[88:89], 0x20000
	s_nop 1
	v_fmamk_f32 v66, v169, 0x3a800000, v228
	v_cmp_gt_f32_e32 vcc, s1, v66
	v_mul_f32_e32 v67, 0x4f800000, v66
	v_lshl_add_u64 v[64:65], v[154:155], 0, s[8:9]
	v_cndmask_b32_e32 v66, v66, v67, vcc
	v_sqrt_f32_e32 v67, v66
	s_nop 0
	v_add_u32_e32 v68, -1, v67
	v_fma_f32 v69, -v68, v67, v66
	v_cmp_ge_f32_e64 s[8:9], 0, v69
	v_add_u32_e32 v69, 1, v67
	s_nop 0
	v_cndmask_b32_e64 v68, v67, v68, s[8:9]
	v_fma_f32 v67, -v69, v67, v66
	v_cmp_lt_f32_e64 s[8:9], 0, v67
	s_nop 1
	v_cndmask_b32_e64 v67, v68, v69, s[8:9]
	v_mul_f32_e32 v68, 0x37800000, v67
	v_cndmask_b32_e32 v67, v67, v68, vcc
	v_cmp_class_f32_e32 vcc, v66, v229
	s_nop 1
	v_cndmask_b32_e32 v66, v67, v66, vcc
	v_div_scale_f32 v67, s[8:9], v66, v66, 1.0
	v_rcp_f32_e32 v68, v67
	s_mov_b32 s8, 0x100000
	v_fma_f32 v69, -v67, v68, 1.0
	v_fmac_f32_e32 v68, v69, v68
	v_div_scale_f32 v69, vcc, 1.0, v66, 1.0
	v_mul_f32_e32 v70, v69, v68
	v_fma_f32 v71, -v67, v70, v69
	v_fmac_f32_e32 v70, v71, v68
	v_fma_f32 v67, -v67, v70, v69
	v_div_fmas_f32 v67, v67, v68, v70
	v_div_fixup_f32 v66, v67, v66, 1.0
	v_pk_fma_f32 v[60:61], v[60:61], v[66:67], v[92:93] op_sel_hi:[1,0,1]
	v_pk_fma_f32 v[56:57], v[56:57], v[66:67], v[88:89] op_sel_hi:[1,0,1]
	v_pk_fma_f32 v[62:63], v[62:63], v[66:67], v[94:95] op_sel_hi:[1,0,1]
	v_pk_fma_f32 v[58:59], v[58:59], v[66:67], v[90:91] op_sel_hi:[1,0,1]
	v_max_f32_e32 v60, 0, v60
	v_max_f32_e32 v56, 0, v56
	v_max_f32_e32 v61, 0, v61
	v_max_f32_e32 v57, 0, v57
	v_pk_mul_f32 v[60:61], v[60:61], v[60:61]
	v_pk_mul_f32 v[68:69], v[56:57], v[56:57]
	v_max_f32_e32 v56, 0, v62
	v_max_f32_e32 v58, 0, v58
	v_max_f32_e32 v57, 0, v63
	v_max_f32_e32 v59, 0, v59
	v_pk_mul_f32 v[62:63], v[56:57], v[56:57]
	v_pk_mul_f32 v[70:71], v[58:59], v[58:59]
	v_cvt_pk_bf16_f32 v56, v60, v61
	v_add_co_u32_e32 v60, vcc, s8, v154
	v_pk_fma_f32 v[48:49], v[48:49], v[66:67], v[80:81] op_sel_hi:[1,0,1]
	v_cvt_pk_bf16_f32 v57, v62, v63
	v_cvt_pk_bf16_f32 v58, v68, v69
	v_cvt_pk_bf16_f32 v59, v70, v71
	v_addc_co_u32_e32 v61, vcc, 0, v155, vcc
	v_pk_fma_f32 v[54:55], v[54:55], v[66:67], v[86:87] op_sel_hi:[1,0,1]
	v_pk_fma_f32 v[52:53], v[52:53], v[66:67], v[84:85] op_sel_hi:[1,0,1]
	v_pk_fma_f32 v[50:51], v[50:51], v[66:67], v[82:83] op_sel_hi:[1,0,1]
	v_max_f32_e32 v48, 0, v48
	v_max_f32_e32 v49, 0, v49
	ds_bpermute_b32 v192, v196, v56
	ds_bpermute_b32 v193, v196, v57
	ds_bpermute_b32 v194, v196, v58
	ds_bpermute_b32 v195, v196, v59
	s_waitcnt lgkmcnt(0)
	global_store_dwordx4 v[226:227], v[192:195], off
	v_max_f32_e32 v52, 0, v52
	v_max_f32_e32 v53, 0, v53
	v_pk_mul_f32 v[56:57], v[48:49], v[48:49]
	v_max_f32_e32 v48, 0, v54
	v_max_f32_e32 v50, 0, v50
	v_max_f32_e32 v49, 0, v55
	v_max_f32_e32 v51, 0, v51
	v_pk_mul_f32 v[52:53], v[52:53], v[52:53]
	v_pk_mul_f32 v[54:55], v[48:49], v[48:49]
	v_pk_mul_f32 v[58:59], v[50:51], v[50:51]
	v_cvt_pk_bf16_f32 v48, v52, v53
	v_cvt_pk_bf16_f32 v49, v54, v55
	v_cvt_pk_bf16_f32 v50, v56, v57
	v_cvt_pk_bf16_f32 v51, v58, v59
	ds_bpermute_b32 v192, v196, v48
	ds_bpermute_b32 v193, v196, v49
	ds_bpermute_b32 v194, v196, v50
	ds_bpermute_b32 v195, v196, v51
	s_waitcnt lgkmcnt(0)
	global_store_dwordx4 v[226:227], v[192:195], off offset:256
	v_lshl_add_u64 v[226:227], v[226:227], 0, s[88:89]
	s_mov_b64 s[8:9], 0x120000
	s_nop 0
	v_fmamk_f32 v50, v168, 0x3a800000, v228
	v_cmp_gt_f32_e32 vcc, s1, v50
	v_mul_f32_e32 v51, 0x4f800000, v50
	v_lshl_add_u64 v[48:49], v[154:155], 0, s[8:9]
	v_cndmask_b32_e32 v50, v50, v51, vcc
	v_sqrt_f32_e32 v51, v50
	s_nop 0
	v_add_u32_e32 v52, -1, v51
	v_fma_f32 v53, -v52, v51, v50
	v_cmp_ge_f32_e64 s[8:9], 0, v53
	v_add_u32_e32 v53, 1, v51
	s_nop 0
	v_cndmask_b32_e64 v52, v51, v52, s[8:9]
	v_fma_f32 v51, -v53, v51, v50
	v_cmp_lt_f32_e64 s[8:9], 0, v51
	s_nop 1
	v_cndmask_b32_e64 v51, v52, v53, s[8:9]
	v_mul_f32_e32 v52, 0x37800000, v51
	v_cndmask_b32_e32 v51, v51, v52, vcc
	v_cmp_class_f32_e32 vcc, v50, v229
	s_nop 1
	v_cndmask_b32_e32 v50, v51, v50, vcc
	v_div_scale_f32 v51, s[8:9], v50, v50, 1.0
	v_rcp_f32_e32 v52, v51
	s_mov_b32 s8, 0x120000
	v_fma_f32 v53, -v51, v52, 1.0
	v_fmac_f32_e32 v52, v53, v52
	v_div_scale_f32 v53, vcc, 1.0, v50, 1.0
	v_mul_f32_e32 v54, v53, v52
	v_fma_f32 v55, -v51, v54, v53
	v_fmac_f32_e32 v54, v55, v52
	v_fma_f32 v51, -v51, v54, v53
	v_div_fmas_f32 v51, v51, v52, v54
	v_div_fixup_f32 v50, v51, v50, 1.0
	v_pk_fma_f32 v[44:45], v[44:45], v[50:51], v[92:93] op_sel_hi:[1,0,1]
	v_pk_fma_f32 v[40:41], v[40:41], v[50:51], v[88:89] op_sel_hi:[1,0,1]
	v_pk_fma_f32 v[46:47], v[46:47], v[50:51], v[94:95] op_sel_hi:[1,0,1]
	v_pk_fma_f32 v[42:43], v[42:43], v[50:51], v[90:91] op_sel_hi:[1,0,1]
	v_max_f32_e32 v44, 0, v44
	v_max_f32_e32 v40, 0, v40
	v_max_f32_e32 v45, 0, v45
	v_max_f32_e32 v41, 0, v41
	v_pk_mul_f32 v[44:45], v[44:45], v[44:45]
	v_pk_mul_f32 v[52:53], v[40:41], v[40:41]
	v_max_f32_e32 v40, 0, v46
	v_max_f32_e32 v42, 0, v42
	v_max_f32_e32 v41, 0, v47
	v_max_f32_e32 v43, 0, v43
	v_pk_mul_f32 v[46:47], v[40:41], v[40:41]
	v_pk_mul_f32 v[54:55], v[42:43], v[42:43]
	v_cvt_pk_bf16_f32 v40, v44, v45
	v_add_co_u32_e32 v44, vcc, s8, v154
	v_pk_fma_f32 v[32:33], v[32:33], v[50:51], v[80:81] op_sel_hi:[1,0,1]
	v_cvt_pk_bf16_f32 v41, v46, v47
	v_cvt_pk_bf16_f32 v42, v52, v53
	v_cvt_pk_bf16_f32 v43, v54, v55
	v_addc_co_u32_e32 v45, vcc, 0, v155, vcc
	v_pk_fma_f32 v[38:39], v[38:39], v[50:51], v[86:87] op_sel_hi:[1,0,1]
	v_pk_fma_f32 v[36:37], v[36:37], v[50:51], v[84:85] op_sel_hi:[1,0,1]
	v_pk_fma_f32 v[34:35], v[34:35], v[50:51], v[82:83] op_sel_hi:[1,0,1]
	v_max_f32_e32 v32, 0, v32
	v_max_f32_e32 v33, 0, v33
	ds_bpermute_b32 v192, v196, v40
	ds_bpermute_b32 v193, v196, v41
	ds_bpermute_b32 v194, v196, v42
	ds_bpermute_b32 v195, v196, v43
	s_waitcnt lgkmcnt(0)
	global_store_dwordx4 v[226:227], v[192:195], off
	v_max_f32_e32 v36, 0, v36
	v_max_f32_e32 v37, 0, v37
	v_pk_mul_f32 v[40:41], v[32:33], v[32:33]
	v_max_f32_e32 v32, 0, v38
	v_max_f32_e32 v34, 0, v34
	v_max_f32_e32 v33, 0, v39
	v_max_f32_e32 v35, 0, v35
	v_pk_mul_f32 v[36:37], v[36:37], v[36:37]
	v_pk_mul_f32 v[38:39], v[32:33], v[32:33]
	v_pk_mul_f32 v[42:43], v[34:35], v[34:35]
	v_cvt_pk_bf16_f32 v32, v36, v37
	v_cvt_pk_bf16_f32 v33, v38, v39
	v_cvt_pk_bf16_f32 v34, v40, v41
	v_cvt_pk_bf16_f32 v35, v42, v43
	ds_bpermute_b32 v192, v196, v32
	ds_bpermute_b32 v193, v196, v33
	ds_bpermute_b32 v194, v196, v34
	ds_bpermute_b32 v195, v196, v35
	s_waitcnt lgkmcnt(0)
	global_store_dwordx4 v[226:227], v[192:195], off offset:256
	v_lshl_add_u64 v[226:227], v[226:227], 0, s[88:89]
	s_mov_b64 s[8:9], 0x140000
	s_nop 0
	v_fmamk_f32 v34, v167, 0x3a800000, v228
	v_cmp_gt_f32_e32 vcc, s1, v34
	v_mul_f32_e32 v35, 0x4f800000, v34
	v_lshl_add_u64 v[32:33], v[154:155], 0, s[8:9]
	v_cndmask_b32_e32 v34, v34, v35, vcc
	v_sqrt_f32_e32 v35, v34
	s_nop 0
	v_add_u32_e32 v36, -1, v35
	v_fma_f32 v37, -v36, v35, v34
	v_cmp_ge_f32_e64 s[8:9], 0, v37
	v_add_u32_e32 v37, 1, v35
	s_nop 0
	v_cndmask_b32_e64 v36, v35, v36, s[8:9]
	v_fma_f32 v35, -v37, v35, v34
	v_cmp_lt_f32_e64 s[8:9], 0, v35
	s_nop 1
	v_cndmask_b32_e64 v35, v36, v37, s[8:9]
	v_mul_f32_e32 v36, 0x37800000, v35
	v_cndmask_b32_e32 v35, v35, v36, vcc
	v_cmp_class_f32_e32 vcc, v34, v229
	s_nop 1
	v_cndmask_b32_e32 v34, v35, v34, vcc
	v_div_scale_f32 v35, s[8:9], v34, v34, 1.0
	v_rcp_f32_e32 v36, v35
	s_mov_b32 s8, 0x140000
	v_fma_f32 v37, -v35, v36, 1.0
	v_fmac_f32_e32 v36, v37, v36
	v_div_scale_f32 v37, vcc, 1.0, v34, 1.0
	v_mul_f32_e32 v38, v37, v36
	v_fma_f32 v39, -v35, v38, v37
	v_fmac_f32_e32 v38, v39, v36
	v_fma_f32 v35, -v35, v38, v37
	v_div_fmas_f32 v35, v35, v36, v38
	v_div_fixup_f32 v34, v35, v34, 1.0
	v_pk_fma_f32 v[28:29], v[28:29], v[34:35], v[92:93] op_sel_hi:[1,0,1]
	v_pk_fma_f32 v[24:25], v[24:25], v[34:35], v[88:89] op_sel_hi:[1,0,1]
	v_pk_fma_f32 v[30:31], v[30:31], v[34:35], v[94:95] op_sel_hi:[1,0,1]
	v_pk_fma_f32 v[26:27], v[26:27], v[34:35], v[90:91] op_sel_hi:[1,0,1]
	v_max_f32_e32 v28, 0, v28
	v_max_f32_e32 v24, 0, v24
	v_max_f32_e32 v29, 0, v29
	v_max_f32_e32 v25, 0, v25
	v_pk_mul_f32 v[28:29], v[28:29], v[28:29]
	v_pk_mul_f32 v[36:37], v[24:25], v[24:25]
	v_max_f32_e32 v24, 0, v30
	v_max_f32_e32 v26, 0, v26
	v_max_f32_e32 v25, 0, v31
	v_max_f32_e32 v27, 0, v27
	v_pk_mul_f32 v[30:31], v[24:25], v[24:25]
	v_pk_mul_f32 v[38:39], v[26:27], v[26:27]
	v_cvt_pk_bf16_f32 v24, v28, v29
	v_add_co_u32_e32 v28, vcc, s8, v154
	v_pk_fma_f32 v[16:17], v[16:17], v[34:35], v[80:81] op_sel_hi:[1,0,1]
	v_cvt_pk_bf16_f32 v25, v30, v31
	v_cvt_pk_bf16_f32 v26, v36, v37
	v_cvt_pk_bf16_f32 v27, v38, v39
	v_addc_co_u32_e32 v29, vcc, 0, v155, vcc
	v_pk_fma_f32 v[22:23], v[22:23], v[34:35], v[86:87] op_sel_hi:[1,0,1]
	v_pk_fma_f32 v[20:21], v[20:21], v[34:35], v[84:85] op_sel_hi:[1,0,1]
	v_pk_fma_f32 v[18:19], v[18:19], v[34:35], v[82:83] op_sel_hi:[1,0,1]
	v_max_f32_e32 v16, 0, v16
	v_max_f32_e32 v17, 0, v17
	ds_bpermute_b32 v192, v196, v24
	ds_bpermute_b32 v193, v196, v25
	ds_bpermute_b32 v194, v196, v26
	ds_bpermute_b32 v195, v196, v27
	s_waitcnt lgkmcnt(0)
	global_store_dwordx4 v[226:227], v[192:195], off
	v_max_f32_e32 v20, 0, v20
	v_max_f32_e32 v21, 0, v21
	v_pk_mul_f32 v[24:25], v[16:17], v[16:17]
	v_max_f32_e32 v16, 0, v22
	v_max_f32_e32 v18, 0, v18
	v_max_f32_e32 v17, 0, v23
	v_max_f32_e32 v19, 0, v19
	v_pk_mul_f32 v[20:21], v[20:21], v[20:21]
	v_pk_mul_f32 v[22:23], v[16:17], v[16:17]
	v_pk_mul_f32 v[26:27], v[18:19], v[18:19]
	v_cvt_pk_bf16_f32 v16, v20, v21
	v_cvt_pk_bf16_f32 v17, v22, v23
	v_cvt_pk_bf16_f32 v18, v24, v25
	v_cvt_pk_bf16_f32 v19, v26, v27
	ds_bpermute_b32 v192, v196, v16
	ds_bpermute_b32 v193, v196, v17
	ds_bpermute_b32 v194, v196, v18
	ds_bpermute_b32 v195, v196, v19
	s_waitcnt lgkmcnt(0)
	global_store_dwordx4 v[226:227], v[192:195], off offset:256
	v_lshl_add_u64 v[226:227], v[226:227], 0, s[88:89]
	s_mov_b64 s[8:9], 0x160000
	s_nop 0
	v_fmamk_f32 v18, v166, 0x3a800000, v228
	v_cmp_gt_f32_e32 vcc, s1, v18
	v_mul_f32_e32 v19, 0x4f800000, v18
	v_lshl_add_u64 v[16:17], v[154:155], 0, s[8:9]
	v_cndmask_b32_e32 v18, v18, v19, vcc
	v_sqrt_f32_e32 v19, v18
	s_nop 0
	v_add_u32_e32 v20, -1, v19
	v_fma_f32 v21, -v20, v19, v18
	v_cmp_ge_f32_e64 s[8:9], 0, v21
	v_add_u32_e32 v21, 1, v19
	s_nop 0
	v_cndmask_b32_e64 v20, v19, v20, s[8:9]
	v_fma_f32 v19, -v21, v19, v18
	v_cmp_lt_f32_e64 s[8:9], 0, v19
	s_nop 1
	v_cndmask_b32_e64 v19, v20, v21, s[8:9]
	v_mul_f32_e32 v20, 0x37800000, v19
	v_cndmask_b32_e32 v19, v19, v20, vcc
	v_cmp_class_f32_e32 vcc, v18, v229
	s_nop 1
	v_cndmask_b32_e32 v18, v19, v18, vcc
	v_div_scale_f32 v19, s[8:9], v18, v18, 1.0
	v_rcp_f32_e32 v20, v19
	s_mov_b32 s8, 0x160000
	v_fma_f32 v21, -v19, v20, 1.0
	v_fmac_f32_e32 v20, v21, v20
	v_div_scale_f32 v21, vcc, 1.0, v18, 1.0
	v_mul_f32_e32 v22, v21, v20
	v_fma_f32 v23, -v19, v22, v21
	v_fmac_f32_e32 v22, v23, v20
	v_fma_f32 v19, -v19, v22, v21
	v_div_fmas_f32 v19, v19, v20, v22
	v_div_fixup_f32 v18, v19, v18, 1.0
	v_pk_fma_f32 v[12:13], v[12:13], v[18:19], v[92:93] op_sel_hi:[1,0,1]
	v_pk_fma_f32 v[8:9], v[8:9], v[18:19], v[88:89] op_sel_hi:[1,0,1]
	v_pk_fma_f32 v[14:15], v[14:15], v[18:19], v[94:95] op_sel_hi:[1,0,1]
	v_pk_fma_f32 v[10:11], v[10:11], v[18:19], v[90:91] op_sel_hi:[1,0,1]
	v_max_f32_e32 v12, 0, v12
	v_max_f32_e32 v8, 0, v8
	v_max_f32_e32 v13, 0, v13
	v_max_f32_e32 v9, 0, v9
	v_pk_mul_f32 v[12:13], v[12:13], v[12:13]
	v_pk_mul_f32 v[20:21], v[8:9], v[8:9]
	v_max_f32_e32 v8, 0, v14
	v_max_f32_e32 v10, 0, v10
	v_max_f32_e32 v9, 0, v15
	v_max_f32_e32 v11, 0, v11
	v_pk_mul_f32 v[14:15], v[8:9], v[8:9]
	v_pk_mul_f32 v[22:23], v[10:11], v[10:11]
	v_cvt_pk_bf16_f32 v8, v12, v13
	v_add_co_u32_e32 v12, vcc, s8, v154
	v_pk_fma_f32 v[0:1], v[0:1], v[18:19], v[80:81] op_sel_hi:[1,0,1]
	v_cvt_pk_bf16_f32 v9, v14, v15
	v_cvt_pk_bf16_f32 v10, v20, v21
	v_cvt_pk_bf16_f32 v11, v22, v23
	v_addc_co_u32_e32 v13, vcc, 0, v155, vcc
	v_pk_fma_f32 v[6:7], v[6:7], v[18:19], v[86:87] op_sel_hi:[1,0,1]
	v_pk_fma_f32 v[4:5], v[4:5], v[18:19], v[84:85] op_sel_hi:[1,0,1]
	v_pk_fma_f32 v[2:3], v[2:3], v[18:19], v[82:83] op_sel_hi:[1,0,1]
	v_max_f32_e32 v0, 0, v0
	v_max_f32_e32 v1, 0, v1
	ds_bpermute_b32 v192, v196, v8
	ds_bpermute_b32 v193, v196, v9
	ds_bpermute_b32 v194, v196, v10
	ds_bpermute_b32 v195, v196, v11
	s_waitcnt lgkmcnt(0)
	global_store_dwordx4 v[226:227], v[192:195], off
	v_max_f32_e32 v4, 0, v4
	v_max_f32_e32 v5, 0, v5
	v_pk_mul_f32 v[8:9], v[0:1], v[0:1]
	v_max_f32_e32 v0, 0, v6
	v_max_f32_e32 v2, 0, v2
	v_max_f32_e32 v1, 0, v7
	v_max_f32_e32 v3, 0, v3
	v_pk_mul_f32 v[4:5], v[4:5], v[4:5]
	v_pk_mul_f32 v[6:7], v[0:1], v[0:1]
	v_pk_mul_f32 v[10:11], v[2:3], v[2:3]
	v_cvt_pk_bf16_f32 v0, v4, v5
	v_cvt_pk_bf16_f32 v1, v6, v7
	v_cvt_pk_bf16_f32 v2, v8, v9
	v_cvt_pk_bf16_f32 v3, v10, v11
	s_mov_b64 s[8:9], -1
	s_andn2_b64 vcc, exec, s[6:7]
	ds_bpermute_b32 v192, v196, v0
	ds_bpermute_b32 v193, v196, v1
	ds_bpermute_b32 v194, v196, v2
	ds_bpermute_b32 v195, v196, v3
	s_waitcnt lgkmcnt(0)
	global_store_dwordx4 v[226:227], v[192:195], off offset:256
	s_cbranch_vccnz .LBB0_1296
	s_andn2_b64 vcc, exec, s[10:11]
	s_cbranch_vccnz .LBB0_1295
	s_barrier
	s_branch .LBB0_1295
